# v68 + G2b cross-tile prefetch (chunk 0 of the next G2b tile issued at the start of the epilogue)
# baseline (speedup 1.0000x reference)
.LBB1_806:
	s_mov_b32 s59, 0
	v_readlane_b32 s2, v242, 62
	s_cmp_ge_i32 s56, s2
	s_cselect_b64 s[4:5], -1, 0
	s_sub_i32 s2, s56, s2
	s_load_dwordx2 s[56:57], s[0:1], 0x1b8
	s_load_dwordx16 s[64:79], s[0:1], 0x100
	s_cmpk_lt_i32 s2, 0x580
	s_cselect_b64 s[6:7], -1, 0
	s_and_b64 s[4:5], s[4:5], s[6:7]
	v_readlane_b32 s14, v241, 36
	s_andn2_b64 vcc, exec, s[4:5]
	v_readlane_b32 s15, v241, 37
	s_cbranch_vccnz .LBB1_810
.LBB1_807:
	s_mul_hi_i32 s4, s2, 0x2e8ba2e9
	s_lshr_b32 s5, s4, 31
	s_ashr_i32 s4, s4, 5
	s_add_i32 s4, s4, s5
	s_mul_i32 s5, s4, 0xb0
	v_mov_b32_e32 v90, v162
	s_sub_i32 s5, s2, s5
	s_load_dwordx16 s[40:55], s[0:1], 0x140
	s_mulk_i32 s5, 0x60
	v_ashrrev_i32_e32 v38, 3, v90
	v_add_u32_e32 v0, s5, v38
	v_ashrrev_i32_e32 v1, 31, v0
	v_lshlrev_b64 v[0:1], 11, v[0:1]
	s_waitcnt lgkmcnt(0)
	v_lshl_add_u64 v[0:1], s[48:49], 0, v[0:1]
	v_lshlrev_b32_e32 v2, 4, v90
	s_load_dwordx16 s[40:55], s[0:1], 0xc0
	s_lshl_b32 s4, s4, 7
	v_and_b32_e32 v128, 0x70, v2
	v_lshl_add_u64 v[76:77], v[0:1], 0, v[128:129]
	v_add_u32_e32 v0, s4, v38
	v_ashrrev_i32_e32 v1, 31, v0
	v_lshlrev_b64 v[0:1], 11, v[0:1]
	s_waitcnt lgkmcnt(0)
	v_lshl_add_u64 v[0:1], s[48:49], 0, v[0:1]
	s_mov_b32 s6, 0x10000
	v_lshl_add_u64 v[78:79], v[0:1], 0, v[128:129]
	v_add_co_u32_e32 v0, vcc, s6, v76
	s_mov_b32 s7, 0x30000
	s_nop 0
	v_addc_co_u32_e32 v1, vcc, 0, v77, vcc
	v_add_co_u32_e32 v30, vcc, s6, v78
	s_mov_b32 s6, 0x20000
	s_nop 0
	v_addc_co_u32_e32 v31, vcc, 0, v79, vcc
	v_add_co_u32_e32 v32, vcc, s6, v78
	s_nop 0
	v_addc_co_u32_e32 v33, vcc, 0, v79, vcc
	v_add_co_u32_e32 v34, vcc, s7, v78
	s_nop 0
	v_addc_co_u32_e32 v35, vcc, 0, v79, vcc
	v_add_co_u32_e32 v36, vcc, s6, v76
	v_addc_co_u32_e32 v37, vcc, 0, v77, vcc
	s_barrier
	v_ashrrev_i32_e32 v30, 7, v90
	s_movk_i32 s8, 0x90
	v_and_b32_e32 v92, 15, v90
	v_bfe_u32 v91, v90, 4, 2
	v_and_b32_e32 v31, 0x4f, v90
	v_mul_lo_u32 v32, v38, s8
	v_mul_lo_u32 v93, v30, 48
	v_lshl_add_u32 v30, v91, 4, 16
	v_mul_u32_u24_e32 v31, 0x90, v31
	v_add3_u32 v94, v128, v32, 16
	v_or_b32_e32 v32, v93, v92
	v_mov_b32_e32 v0, 0
	v_add_u32_e32 v95, v30, v31
	v_mul_lo_u32 v31, v32, s8
	s_mov_b64 s[8:9], 0x10000
	s_mov_b64 s[10:11], 0x20000
	s_mov_b64 s[12:13], 0x30000
	s_mov_b32 s7, 0
	s_movk_i32 s6, 0x80
	v_mov_b32_e32 v1, v0
	v_add_u32_e32 v96, 0xd800, v94
	v_add_u32_e32 v97, v30, v31
	v_lshl_add_u64 v[80:81], v[78:79], 0, s[8:9]
	v_lshl_add_u64 v[82:83], v[78:79], 0, s[10:11]
	v_lshl_add_u64 v[84:85], v[78:79], 0, s[12:13]
	v_lshl_add_u64 v[86:87], v[76:77], 0, s[8:9]
	v_lshl_add_u64 v[88:89], v[76:77], 0, s[10:11]
	v_mov_b32_e32 v30, v0
	v_mov_b32_e32 v31, v0
	v_mov_b32_e32 v32, v0
	v_mov_b32_e32 v33, v0
	v_mov_b32_e32 v34, v0
	v_mov_b32_e32 v35, v0
	v_mov_b32_e32 v36, v0
	v_mov_b32_e32 v37, v0
	v_mov_b32_e32 v38, v0
	v_mov_b32_e32 v39, v0
	v_mov_b32_e32 v40, v0
	v_mov_b32_e32 v41, v0
	v_mov_b32_e32 v42, v0
	v_mov_b32_e32 v43, v0
	v_mov_b32_e32 v72, v0
	v_mov_b32_e32 v73, v0
	v_mov_b32_e32 v74, v0
	v_mov_b32_e32 v75, v0
	s_waitcnt vmcnt(12)
	s_waitcnt vmcnt(11)
	s_waitcnt vmcnt(10)
	s_waitcnt vmcnt(9)
	s_waitcnt vmcnt(8)
	s_waitcnt vmcnt(7)
	v_mov_b32_e32 v2, v0
	v_mov_b32_e32 v3, v0
	v_mov_b32_e32 v4, v0
	v_mov_b32_e32 v5, v0
	v_mov_b32_e32 v6, v0
	v_mov_b32_e32 v7, v0
	v_mov_b32_e32 v8, v0
	v_mov_b32_e32 v9, v0
	v_mov_b32_e32 v10, v0
	v_mov_b32_e32 v11, v0
	v_mov_b32_e32 v12, v0
	v_mov_b32_e32 v13, v0
	v_mov_b32_e32 v14, v0
	v_mov_b32_e32 v15, v0
	v_mov_b32_e32 v16, v0
	v_mov_b32_e32 v17, v0
	v_mov_b32_e32 v18, v0
	v_mov_b32_e32 v19, v0
	v_mov_b32_e32 v20, v0
	v_mov_b32_e32 v21, v0
	v_mov_b32_e32 v22, v0
	v_mov_b32_e32 v23, v0
	v_mov_b32_e32 v24, v0
	v_mov_b32_e32 v25, v0
	v_mov_b32_e32 v26, v0
	v_mov_b32_e32 v27, v0
	v_mov_b32_e32 v28, v0
	v_mov_b32_e32 v29, v0
	s_waitcnt lgkmcnt(0)
	s_barrier
	v_and_b32_e32 v204, 15, v168
	v_lshrrev_b32_e32 v205, 4, v168
	v_bfe_u32 v206, v168, 1, 3
	v_xor_b32_e32 v205, v205, v206
	v_lshlrev_b32_e32 v205, 4, v205
	v_readfirstlane_b32 s19, v162
	v_readfirstlane_b32 s8, v76
	v_readfirstlane_b32 s9, v77
	v_readfirstlane_b32 s10, v78
	v_readfirstlane_b32 s11, v79
	s_lshr_b32 s19, s19, 6
	s_lshr_b32 s16, s19, 1
	s_and_b32 s17, s19, 1
	s_mul_i32 s16, s16, 48
	v_add_u32_e32 v206, s16, v204
	v_lshl_add_u32 v232, v206, 7, v205
	v_xor_b32_e32 v233, 64, v232
	v_add_u32_e32 v232, 16, v232
	v_add_u32_e32 v233, 16, v233
	v_lshl_add_u32 v206, s17, 6, v204
	v_lshl_add_u32 v234, v206, 7, v205
	v_xor_b32_e32 v235, 64, v234
	v_add_u32_e32 v234, 0x3010, v234
	v_add_u32_e32 v235, 0x3010, v235
	v_lshrrev_b32_e32 v206, 3, v168
	v_and_b32_e32 v207, 7, v168
	v_lshrrev_b32_e32 v204, 1, v206
	v_xor_b32_e32 v207, v207, v204
	v_lshlrev_b32_e32 v207, 4, v207
	v_lshl_add_u32 v236, v206, 11, v207
	v_xor_b32_e32 v237, 64, v236
	s_and_b32 s17, s19, 1
	s_cmp_eq_u32 s17, 0
	s_cselect_b64 vcc, -1, 0
	s_nop 3
	v_cndmask_b32_e32 v238, v237, v236, vcc
	v_cndmask_b32_e32 v239, v236, v237, vcc
	s_mul_i32 s16, s19, 0x8000
	s_add_u32 s8, s8, s16
	s_addc_u32 s9, s9, 0
	s_mul_i32 s16, s19, 0xc000
	s_add_u32 s10, s10, s16
	s_addc_u32 s11, s11, 0
	s_mul_i32 s16, s19, 0xc00
	s_lshl_b32 s17, s19, 12
	s_cmp_eq_u32 s59, 1
	s_cbranch_scc1 .Lg96pf_skip_LBB1_808
	s_add_i32 m0, s16, 0x10
	s_nop 0
	global_load_lds_dwordx4 v238, s[8:9]
	s_add_i32 m0, s16, 0x410
	s_add_u32 s12, s8, 0x4000
	s_addc_u32 s13, s9, 0
	global_load_lds_dwordx4 v239, s[12:13]
	s_add_i32 m0, s16, 0x810
	s_add_u32 s12, s8, 0x8000
	s_addc_u32 s13, s9, 0
	global_load_lds_dwordx4 v238, s[12:13]
	s_add_i32 m0, s17, 0x3010
	s_nop 0
	global_load_lds_dwordx4 v236, s[10:11]
	s_add_i32 m0, s17, 0x3410
	s_add_u32 s12, s10, 0x4000
	s_addc_u32 s13, s11, 0
	global_load_lds_dwordx4 v237, s[12:13]
	s_add_i32 m0, s17, 0x3810
	s_add_u32 s12, s10, 0x8000
	s_addc_u32 s13, s11, 0
	global_load_lds_dwordx4 v236, s[12:13]
	s_add_i32 m0, s17, 0x3c10
	s_add_u32 s12, s10, 0xc000
	s_addc_u32 s13, s11, 0
	global_load_lds_dwordx4 v237, s[12:13]

.LBB1_808:
	s_lshl_b32 s19, s18, 8
	s_add_i32 s19, s19, 0x80
	s_min_u32 s19, s19, 0x780
	s_add_u32 s40, s8, s19
	s_addc_u32 s41, s9, 0
	s_add_u32 s42, s10, s19
	s_addc_u32 s43, s11, 0
	ds_read_b128 v[142:145], v234 offset:0
	ds_read_b128 v[146:149], v234 offset:2048
	ds_read_b128 v[150:153], v234 offset:4096
	ds_read_b128 v[154:157], v234 offset:6144
	ds_read_b128 v[130:133], v232 offset:0
	ds_read_b128 v[134:137], v232 offset:2048
	ds_read_b128 v[138:141], v232 offset:4096
	ds_read_b128 v[216:219], v235 offset:0
	ds_read_b128 v[220:223], v235 offset:2048
	ds_read_b128 v[224:227], v235 offset:4096
	ds_read_b128 v[228:231], v235 offset:6144
	ds_read_b128 v[188:191], v233 offset:0
	ds_read_b128 v[192:195], v233 offset:2048
	ds_read_b128 v[196:199], v233 offset:4096
	s_waitcnt lgkmcnt(9)
	s_add_i32 m0, s16, 0x7010
	s_nop 0
	v_mfma_f32_16x16x32_bf16 v[72:75], v[142:145], v[130:133], v[72:75]
	global_load_lds_dwordx4 v238, s[40:41]
	s_add_i32 m0, s16, 0x7410
	s_add_u32 s12, s40, 0x4000
	s_addc_u32 s13, s41, 0
	v_mfma_f32_16x16x32_bf16 v[40:43], v[146:149], v[130:133], v[40:43]
	global_load_lds_dwordx4 v239, s[12:13]
	v_mfma_f32_16x16x32_bf16 v[36:39], v[150:153], v[130:133], v[36:39]
	v_mfma_f32_16x16x32_bf16 v[32:35], v[154:157], v[130:133], v[32:35]
	s_waitcnt lgkmcnt(8)
	s_add_i32 m0, s16, 0x7810
	s_add_u32 s12, s40, 0x8000
	s_addc_u32 s13, s41, 0
	v_mfma_f32_16x16x32_bf16 v[28:31], v[142:145], v[134:137], v[28:31]
	v_mfma_f32_16x16x32_bf16 v[24:27], v[146:149], v[134:137], v[24:27]
	global_load_lds_dwordx4 v238, s[12:13]
	v_mfma_f32_16x16x32_bf16 v[20:23], v[150:153], v[134:137], v[20:23]
	v_mfma_f32_16x16x32_bf16 v[16:19], v[154:157], v[134:137], v[16:19]
	s_waitcnt lgkmcnt(7)
	s_add_i32 m0, s17, 0xa010
	s_nop 0
	v_mfma_f32_16x16x32_bf16 v[12:15], v[142:145], v[138:141], v[12:15]
	v_mfma_f32_16x16x32_bf16 v[8:11], v[146:149], v[138:141], v[8:11]
	global_load_lds_dwordx4 v236, s[42:43]
	v_mfma_f32_16x16x32_bf16 v[4:7], v[150:153], v[138:141], v[4:7]
	v_mfma_f32_16x16x32_bf16 v[0:3], v[154:157], v[138:141], v[0:3]
	s_waitcnt lgkmcnt(2)
	s_add_i32 m0, s17, 0xa410
	s_add_u32 s12, s42, 0x4000
	s_addc_u32 s13, s43, 0
	v_mfma_f32_16x16x32_bf16 v[72:75], v[216:219], v[188:191], v[72:75]
	v_mfma_f32_16x16x32_bf16 v[40:43], v[220:223], v[188:191], v[40:43]
	global_load_lds_dwordx4 v237, s[12:13]
	v_mfma_f32_16x16x32_bf16 v[36:39], v[224:227], v[188:191], v[36:39]
	v_mfma_f32_16x16x32_bf16 v[32:35], v[228:231], v[188:191], v[32:35]
	s_waitcnt lgkmcnt(1)
	s_add_i32 m0, s17, 0xa810
	s_add_u32 s12, s42, 0x8000
	s_addc_u32 s13, s43, 0
	v_mfma_f32_16x16x32_bf16 v[28:31], v[216:219], v[192:195], v[28:31]
	v_mfma_f32_16x16x32_bf16 v[24:27], v[220:223], v[192:195], v[24:27]
	global_load_lds_dwordx4 v236, s[12:13]
	v_mfma_f32_16x16x32_bf16 v[20:23], v[224:227], v[192:195], v[20:23]
	v_mfma_f32_16x16x32_bf16 v[16:19], v[228:231], v[192:195], v[16:19]
	s_waitcnt lgkmcnt(0)
	s_add_i32 m0, s17, 0xac10
	s_add_u32 s12, s42, 0xc000
	s_addc_u32 s13, s43, 0
	v_mfma_f32_16x16x32_bf16 v[12:15], v[216:219], v[196:199], v[12:15]
	v_mfma_f32_16x16x32_bf16 v[8:11], v[220:223], v[196:199], v[8:11]
	global_load_lds_dwordx4 v237, s[12:13]
	v_mfma_f32_16x16x32_bf16 v[4:7], v[224:227], v[196:199], v[4:7]
	v_mfma_f32_16x16x32_bf16 v[0:3], v[228:231], v[196:199], v[0:3]
	s_waitcnt vmcnt(0)
	s_barrier
	s_lshl_b32 s19, s18, 8
	s_add_i32 s19, s19, 0x100
	s_min_u32 s19, s19, 0x780
	s_add_u32 s40, s8, s19
	s_addc_u32 s41, s9, 0
	s_add_u32 s42, s10, s19
	s_addc_u32 s43, s11, 0
	ds_read_b128 v[142:145], v234 offset:28672
	ds_read_b128 v[146:149], v234 offset:30720
	ds_read_b128 v[150:153], v234 offset:32768
	ds_read_b128 v[154:157], v234 offset:34816
	ds_read_b128 v[130:133], v232 offset:28672
	ds_read_b128 v[134:137], v232 offset:30720
	ds_read_b128 v[138:141], v232 offset:32768
	ds_read_b128 v[216:219], v235 offset:28672
	ds_read_b128 v[220:223], v235 offset:30720
	ds_read_b128 v[224:227], v235 offset:32768
	ds_read_b128 v[228:231], v235 offset:34816
	ds_read_b128 v[188:191], v233 offset:28672
	ds_read_b128 v[192:195], v233 offset:30720
	ds_read_b128 v[196:199], v233 offset:32768
	s_waitcnt lgkmcnt(9)
	s_add_i32 m0, s16, 0x10
	s_nop 0
	v_mfma_f32_16x16x32_bf16 v[72:75], v[142:145], v[130:133], v[72:75]
	global_load_lds_dwordx4 v238, s[40:41]
	s_add_i32 m0, s16, 0x410
	s_add_u32 s12, s40, 0x4000
	s_addc_u32 s13, s41, 0
	v_mfma_f32_16x16x32_bf16 v[40:43], v[146:149], v[130:133], v[40:43]
	global_load_lds_dwordx4 v239, s[12:13]
	v_mfma_f32_16x16x32_bf16 v[36:39], v[150:153], v[130:133], v[36:39]
	v_mfma_f32_16x16x32_bf16 v[32:35], v[154:157], v[130:133], v[32:35]
	s_waitcnt lgkmcnt(8)
	s_add_i32 m0, s16, 0x810
	s_add_u32 s12, s40, 0x8000
	s_addc_u32 s13, s41, 0
	v_mfma_f32_16x16x32_bf16 v[28:31], v[142:145], v[134:137], v[28:31]
	v_mfma_f32_16x16x32_bf16 v[24:27], v[146:149], v[134:137], v[24:27]
	global_load_lds_dwordx4 v238, s[12:13]
	v_mfma_f32_16x16x32_bf16 v[20:23], v[150:153], v[134:137], v[20:23]
	v_mfma_f32_16x16x32_bf16 v[16:19], v[154:157], v[134:137], v[16:19]
	s_waitcnt lgkmcnt(7)
	s_add_i32 m0, s17, 0x3010
	s_nop 0
	v_mfma_f32_16x16x32_bf16 v[12:15], v[142:145], v[138:141], v[12:15]
	v_mfma_f32_16x16x32_bf16 v[8:11], v[146:149], v[138:141], v[8:11]
	global_load_lds_dwordx4 v236, s[42:43]
	v_mfma_f32_16x16x32_bf16 v[4:7], v[150:153], v[138:141], v[4:7]
	v_mfma_f32_16x16x32_bf16 v[0:3], v[154:157], v[138:141], v[0:3]
	s_waitcnt lgkmcnt(2)
	s_add_i32 m0, s17, 0x3410
	s_add_u32 s12, s42, 0x4000
	s_addc_u32 s13, s43, 0
	v_mfma_f32_16x16x32_bf16 v[72:75], v[216:219], v[188:191], v[72:75]
	v_mfma_f32_16x16x32_bf16 v[40:43], v[220:223], v[188:191], v[40:43]
	global_load_lds_dwordx4 v237, s[12:13]
	v_mfma_f32_16x16x32_bf16 v[36:39], v[224:227], v[188:191], v[36:39]
	v_mfma_f32_16x16x32_bf16 v[32:35], v[228:231], v[188:191], v[32:35]
	s_waitcnt lgkmcnt(1)
	s_add_i32 m0, s17, 0x3810
	s_add_u32 s12, s42, 0x8000
	s_addc_u32 s13, s43, 0
	v_mfma_f32_16x16x32_bf16 v[28:31], v[216:219], v[192:195], v[28:31]
	v_mfma_f32_16x16x32_bf16 v[24:27], v[220:223], v[192:195], v[24:27]
	global_load_lds_dwordx4 v236, s[12:13]
	v_mfma_f32_16x16x32_bf16 v[20:23], v[224:227], v[192:195], v[20:23]
	v_mfma_f32_16x16x32_bf16 v[16:19], v[228:231], v[192:195], v[16:19]
	s_waitcnt lgkmcnt(0)
	s_add_i32 m0, s17, 0x3c10
	s_add_u32 s12, s42, 0xc000
	s_addc_u32 s13, s43, 0
	v_mfma_f32_16x16x32_bf16 v[12:15], v[216:219], v[196:199], v[12:15]
	v_mfma_f32_16x16x32_bf16 v[8:11], v[220:223], v[196:199], v[8:11]
	global_load_lds_dwordx4 v237, s[12:13]
	v_mfma_f32_16x16x32_bf16 v[4:7], v[224:227], v[196:199], v[4:7]
	v_mfma_f32_16x16x32_bf16 v[0:3], v[228:231], v[196:199], v[0:3]
	s_waitcnt vmcnt(0)
	s_barrier
	s_add_i32 s18, s18, 1
	s_cmp_eq_u32 s18, 8
	s_cbranch_scc0 .LBB1_808
	s_setprio 0
	s_waitcnt vmcnt(0)
	v_readlane_b32 s30, v242, 63
	s_nop 1
	s_add_i32 s31, s2, s30
	s_cmp_lt_u32 s31, 0x580
	s_cselect_b32 s59, 1, 0
	s_cbranch_scc0 .Lg96pf_none_g2b
	s_mul_i32 s38, s31, 745
	s_lshr_b32 s38, s38, 17
	s_mul_i32 s39, s38, 176
	s_sub_i32 s39, s31, s39
	s_mul_i32 s30, s39, 96
	s_sub_i32 s30, s30, s5
	s_ashr_i32 s31, s30, 31
	s_lshl_b64 s[30:31], s[30:31], 11
	s_add_u32 s88, s8, s30
	s_addc_u32 s89, s9, s31
	s_lshl_b32 s24, s38, 7
	s_sub_i32 s24, s24, s4
	s_ashr_i32 s25, s24, 31
	s_lshl_b64 s[24:25], s[24:25], 11
	s_add_u32 s90, s10, s24
	s_addc_u32 s91, s11, s25
	s_add_i32 m0, s16, 0x10
	s_nop 0
	global_load_lds_dwordx4 v238, s[88:89]
	s_add_i32 m0, s16, 0x410
	s_add_u32 s30, s88, 0x4000
	s_addc_u32 s31, s89, 0
	global_load_lds_dwordx4 v239, s[30:31]
	s_add_i32 m0, s16, 0x810
	s_add_u32 s30, s88, 0x8000
	s_addc_u32 s31, s89, 0
	global_load_lds_dwordx4 v238, s[30:31]
	s_add_i32 m0, s17, 0x3010
	s_nop 0
	global_load_lds_dwordx4 v236, s[90:91]
	s_add_i32 m0, s17, 0x3410
	s_add_u32 s30, s90, 0x4000
	s_addc_u32 s31, s91, 0
	global_load_lds_dwordx4 v237, s[30:31]
	s_add_i32 m0, s17, 0x3810
	s_add_u32 s30, s90, 0x8000
	s_addc_u32 s31, s91, 0
	global_load_lds_dwordx4 v236, s[30:31]
	s_add_i32 m0, s17, 0x3c10
	s_add_u32 s30, s90, 0xc000
	s_addc_u32 s31, s91, 0
	global_load_lds_dwordx4 v237, s[30:31]
.Lg96pf_none_g2b:
	v_and_b32_e32 v154, 15, v168
	v_lshrrev_b32_e32 v155, 4, v168
	v_lshrrev_b32_e32 v156, 7, v162
	v_bfe_u32 v157, v162, 6, 1
	v_mul_u32_u24_e32 v156, 48, v156
	v_add3_u32 v156, v156, v154, s5
	v_lshlrev_b32_e32 v157, 6, v157
	v_lshl_add_u32 v157, v155, 2, v157
	v_add_u32_e32 v157, s4, v157
	v_lshlrev_b32_e32 v53, 2, v157
	v_lshlrev_b32_e32 v158, 1, v157
	v_lshl_add_u32 v44, v156, 14, v158
	v_lshl_add_u32 v47, v156, 12, v53
	v_add_u32_e32 v156, 16, v156
	v_lshlrev_b32_e32 v158, 1, v157
	v_lshl_add_u32 v45, v156, 14, v158
	v_lshl_add_u32 v48, v156, 12, v53
	v_add_u32_e32 v156, 16, v156
	v_lshlrev_b32_e32 v158, 1, v157
	v_lshl_add_u32 v46, v156, 14, v158
	v_lshl_add_u32 v49, v156, 12, v53
	s_add_u32 s10, s76, 0x3800
	s_addc_u32 s11, s77, 0
	global_load_dwordx4 v[54:57], v53, s[14:15] offset:0
	global_load_dwordx4 v[58:61], v53, s[14:15] offset:64
	global_load_dwordx4 v[62:65], v53, s[14:15] offset:128
	global_load_dwordx4 v[66:69], v53, s[14:15] offset:192
	global_load_dwordx2 v[188:189], v44, s[10:11] offset:0
	global_load_dwordx2 v[190:191], v44, s[10:11] offset:32
	global_load_dwordx2 v[192:193], v44, s[10:11] offset:64
	global_load_dwordx2 v[194:195], v44, s[10:11] offset:96
	global_load_dwordx2 v[196:197], v45, s[10:11] offset:0
	global_load_dwordx2 v[198:199], v45, s[10:11] offset:32
	global_load_dwordx2 v[200:201], v45, s[10:11] offset:64
	global_load_dwordx2 v[202:203], v45, s[10:11] offset:96
	global_load_dwordx2 v[204:205], v46, s[10:11] offset:0
	global_load_dwordx2 v[206:207], v46, s[10:11] offset:32
	global_load_dwordx2 v[208:209], v46, s[10:11] offset:64
	global_load_dwordx2 v[210:211], v46, s[10:11] offset:96
	s_waitcnt vmcnt(11)
	v_lshlrev_b32_e32 v150, 16, v188
	v_and_b32_e32 v151, 0xffff0000, v188
	v_lshlrev_b32_e32 v152, 16, v189
	v_and_b32_e32 v153, 0xffff0000, v189
	v_pk_add_f32 v[150:151], v[54:55], v[150:151]
	v_pk_add_f32 v[152:153], v[56:57], v[152:153]
	s_nop 0
	v_mul_f32_e32 v150, 0xbfb8aa3b, v150
	v_mul_f32_e32 v151, 0xbfb8aa3b, v151
	v_mul_f32_e32 v152, 0xbfb8aa3b, v152
	v_mul_f32_e32 v153, 0xbfb8aa3b, v153
	v_exp_f32_e32 v150, v150
	v_exp_f32_e32 v151, v151
	v_exp_f32_e32 v152, v152
	v_exp_f32_e32 v153, v153
	v_add_f32_e32 v150, 1.0, v150
	v_add_f32_e32 v151, 1.0, v151
	v_add_f32_e32 v152, 1.0, v152
	v_add_f32_e32 v153, 1.0, v153
	v_rcp_f32_e32 v150, v150
	v_rcp_f32_e32 v151, v151
	v_rcp_f32_e32 v152, v152
	v_rcp_f32_e32 v153, v153
	v_pk_mul_f32 v[72:73], v[72:73], v[150:151]
	v_pk_mul_f32 v[74:75], v[74:75], v[152:153]
	s_nop 0
	global_store_dwordx4 v47, v[72:75], s[72:73] offset:0
	s_waitcnt vmcnt(10)
	v_lshlrev_b32_e32 v150, 16, v190
	v_and_b32_e32 v151, 0xffff0000, v190
	v_lshlrev_b32_e32 v152, 16, v191
	v_and_b32_e32 v153, 0xffff0000, v191
	v_pk_add_f32 v[150:151], v[58:59], v[150:151]
	v_pk_add_f32 v[152:153], v[60:61], v[152:153]
	s_nop 0
	v_mul_f32_e32 v150, 0xbfb8aa3b, v150
	v_mul_f32_e32 v151, 0xbfb8aa3b, v151
	v_mul_f32_e32 v152, 0xbfb8aa3b, v152
	v_mul_f32_e32 v153, 0xbfb8aa3b, v153
	v_exp_f32_e32 v150, v150
	v_exp_f32_e32 v151, v151
	v_exp_f32_e32 v152, v152
	v_exp_f32_e32 v153, v153
	v_add_f32_e32 v150, 1.0, v150
	v_add_f32_e32 v151, 1.0, v151
	v_add_f32_e32 v152, 1.0, v152
	v_add_f32_e32 v153, 1.0, v153
	v_rcp_f32_e32 v150, v150
	v_rcp_f32_e32 v151, v151
	v_rcp_f32_e32 v152, v152
	v_rcp_f32_e32 v153, v153
	v_pk_mul_f32 v[40:41], v[40:41], v[150:151]
	v_pk_mul_f32 v[42:43], v[42:43], v[152:153]
	s_nop 0
	global_store_dwordx4 v47, v[40:43], s[72:73] offset:64
	s_waitcnt vmcnt(9)
	v_lshlrev_b32_e32 v150, 16, v192
	v_and_b32_e32 v151, 0xffff0000, v192
	v_lshlrev_b32_e32 v152, 16, v193
	v_and_b32_e32 v153, 0xffff0000, v193
	v_pk_add_f32 v[150:151], v[62:63], v[150:151]
	v_pk_add_f32 v[152:153], v[64:65], v[152:153]
	s_nop 0
	v_mul_f32_e32 v150, 0xbfb8aa3b, v150
	v_mul_f32_e32 v151, 0xbfb8aa3b, v151
	v_mul_f32_e32 v152, 0xbfb8aa3b, v152
	v_mul_f32_e32 v153, 0xbfb8aa3b, v153
	v_exp_f32_e32 v150, v150
	v_exp_f32_e32 v151, v151
	v_exp_f32_e32 v152, v152
	v_exp_f32_e32 v153, v153
	v_add_f32_e32 v150, 1.0, v150
	v_add_f32_e32 v151, 1.0, v151
	v_add_f32_e32 v152, 1.0, v152
	v_add_f32_e32 v153, 1.0, v153
	v_rcp_f32_e32 v150, v150
	v_rcp_f32_e32 v151, v151
	v_rcp_f32_e32 v152, v152
	v_rcp_f32_e32 v153, v153
	v_pk_mul_f32 v[36:37], v[36:37], v[150:151]
	v_pk_mul_f32 v[38:39], v[38:39], v[152:153]
	s_nop 0
	global_store_dwordx4 v47, v[36:39], s[72:73] offset:128
	s_waitcnt vmcnt(8)
	v_lshlrev_b32_e32 v150, 16, v194
	v_and_b32_e32 v151, 0xffff0000, v194
	v_lshlrev_b32_e32 v152, 16, v195
	v_and_b32_e32 v153, 0xffff0000, v195
	v_pk_add_f32 v[150:151], v[66:67], v[150:151]
	v_pk_add_f32 v[152:153], v[68:69], v[152:153]
	s_nop 0
	v_mul_f32_e32 v150, 0xbfb8aa3b, v150
	v_mul_f32_e32 v151, 0xbfb8aa3b, v151
	v_mul_f32_e32 v152, 0xbfb8aa3b, v152
	v_mul_f32_e32 v153, 0xbfb8aa3b, v153
	v_exp_f32_e32 v150, v150
	v_exp_f32_e32 v151, v151
	v_exp_f32_e32 v152, v152
	v_exp_f32_e32 v153, v153
	v_add_f32_e32 v150, 1.0, v150
	v_add_f32_e32 v151, 1.0, v151
	v_add_f32_e32 v152, 1.0, v152
	v_add_f32_e32 v153, 1.0, v153
	v_rcp_f32_e32 v150, v150
	v_rcp_f32_e32 v151, v151
	v_rcp_f32_e32 v152, v152
	v_rcp_f32_e32 v153, v153
	v_pk_mul_f32 v[32:33], v[32:33], v[150:151]
	v_pk_mul_f32 v[34:35], v[34:35], v[152:153]
	s_nop 0
	global_store_dwordx4 v47, v[32:35], s[72:73] offset:192
	s_waitcnt vmcnt(7)
	v_lshlrev_b32_e32 v150, 16, v196
	v_and_b32_e32 v151, 0xffff0000, v196
	v_lshlrev_b32_e32 v152, 16, v197
	v_and_b32_e32 v153, 0xffff0000, v197
	v_pk_add_f32 v[150:151], v[54:55], v[150:151]
	v_pk_add_f32 v[152:153], v[56:57], v[152:153]
	s_nop 0
	v_mul_f32_e32 v150, 0xbfb8aa3b, v150
	v_mul_f32_e32 v151, 0xbfb8aa3b, v151
	v_mul_f32_e32 v152, 0xbfb8aa3b, v152
	v_mul_f32_e32 v153, 0xbfb8aa3b, v153
	v_exp_f32_e32 v150, v150
	v_exp_f32_e32 v151, v151
	v_exp_f32_e32 v152, v152
	v_exp_f32_e32 v153, v153
	v_add_f32_e32 v150, 1.0, v150
	v_add_f32_e32 v151, 1.0, v151
	v_add_f32_e32 v152, 1.0, v152
	v_add_f32_e32 v153, 1.0, v153
	v_rcp_f32_e32 v150, v150
	v_rcp_f32_e32 v151, v151
	v_rcp_f32_e32 v152, v152
	v_rcp_f32_e32 v153, v153
	v_pk_mul_f32 v[28:29], v[28:29], v[150:151]
	v_pk_mul_f32 v[30:31], v[30:31], v[152:153]
	s_nop 0
	global_store_dwordx4 v48, v[28:31], s[72:73] offset:0
	s_waitcnt vmcnt(6)
	v_lshlrev_b32_e32 v150, 16, v198
	v_and_b32_e32 v151, 0xffff0000, v198
	v_lshlrev_b32_e32 v152, 16, v199
	v_and_b32_e32 v153, 0xffff0000, v199
	v_pk_add_f32 v[150:151], v[58:59], v[150:151]
	v_pk_add_f32 v[152:153], v[60:61], v[152:153]
	s_nop 0
	v_mul_f32_e32 v150, 0xbfb8aa3b, v150
	v_mul_f32_e32 v151, 0xbfb8aa3b, v151
	v_mul_f32_e32 v152, 0xbfb8aa3b, v152
	v_mul_f32_e32 v153, 0xbfb8aa3b, v153
	v_exp_f32_e32 v150, v150
	v_exp_f32_e32 v151, v151
	v_exp_f32_e32 v152, v152
	v_exp_f32_e32 v153, v153
	v_add_f32_e32 v150, 1.0, v150
	v_add_f32_e32 v151, 1.0, v151
	v_add_f32_e32 v152, 1.0, v152
	v_add_f32_e32 v153, 1.0, v153
	v_rcp_f32_e32 v150, v150
	v_rcp_f32_e32 v151, v151
	v_rcp_f32_e32 v152, v152
	v_rcp_f32_e32 v153, v153
	v_pk_mul_f32 v[24:25], v[24:25], v[150:151]
	v_pk_mul_f32 v[26:27], v[26:27], v[152:153]
	s_nop 0
	global_store_dwordx4 v48, v[24:27], s[72:73] offset:64
	s_waitcnt vmcnt(5)
	v_lshlrev_b32_e32 v150, 16, v200
	v_and_b32_e32 v151, 0xffff0000, v200
	v_lshlrev_b32_e32 v152, 16, v201
	v_and_b32_e32 v153, 0xffff0000, v201
	v_pk_add_f32 v[150:151], v[62:63], v[150:151]
	v_pk_add_f32 v[152:153], v[64:65], v[152:153]
	s_nop 0
	v_mul_f32_e32 v150, 0xbfb8aa3b, v150
	v_mul_f32_e32 v151, 0xbfb8aa3b, v151
	v_mul_f32_e32 v152, 0xbfb8aa3b, v152
	v_mul_f32_e32 v153, 0xbfb8aa3b, v153
	v_exp_f32_e32 v150, v150
	v_exp_f32_e32 v151, v151
	v_exp_f32_e32 v152, v152
	v_exp_f32_e32 v153, v153
	v_add_f32_e32 v150, 1.0, v150
	v_add_f32_e32 v151, 1.0, v151
	v_add_f32_e32 v152, 1.0, v152
	v_add_f32_e32 v153, 1.0, v153
	v_rcp_f32_e32 v150, v150
	v_rcp_f32_e32 v151, v151
	v_rcp_f32_e32 v152, v152
	v_rcp_f32_e32 v153, v153
	v_pk_mul_f32 v[20:21], v[20:21], v[150:151]
	v_pk_mul_f32 v[22:23], v[22:23], v[152:153]
	s_nop 0
	global_store_dwordx4 v48, v[20:23], s[72:73] offset:128
	s_waitcnt vmcnt(4)
	v_lshlrev_b32_e32 v150, 16, v202
	v_and_b32_e32 v151, 0xffff0000, v202
	v_lshlrev_b32_e32 v152, 16, v203
	v_and_b32_e32 v153, 0xffff0000, v203
	v_pk_add_f32 v[150:151], v[66:67], v[150:151]
	v_pk_add_f32 v[152:153], v[68:69], v[152:153]
	s_nop 0
	v_mul_f32_e32 v150, 0xbfb8aa3b, v150
	v_mul_f32_e32 v151, 0xbfb8aa3b, v151
	v_mul_f32_e32 v152, 0xbfb8aa3b, v152
	v_mul_f32_e32 v153, 0xbfb8aa3b, v153
	v_exp_f32_e32 v150, v150
	v_exp_f32_e32 v151, v151
	v_exp_f32_e32 v152, v152
	v_exp_f32_e32 v153, v153
	v_add_f32_e32 v150, 1.0, v150
	v_add_f32_e32 v151, 1.0, v151
	v_add_f32_e32 v152, 1.0, v152
	v_add_f32_e32 v153, 1.0, v153
	v_rcp_f32_e32 v150, v150
	v_rcp_f32_e32 v151, v151
	v_rcp_f32_e32 v152, v152
	v_rcp_f32_e32 v153, v153
	v_pk_mul_f32 v[16:17], v[16:17], v[150:151]
	v_pk_mul_f32 v[18:19], v[18:19], v[152:153]
	s_nop 0
	global_store_dwordx4 v48, v[16:19], s[72:73] offset:192
	s_waitcnt vmcnt(3)
	v_lshlrev_b32_e32 v150, 16, v204
	v_and_b32_e32 v151, 0xffff0000, v204
	v_lshlrev_b32_e32 v152, 16, v205
	v_and_b32_e32 v153, 0xffff0000, v205
	v_pk_add_f32 v[150:151], v[54:55], v[150:151]
	v_pk_add_f32 v[152:153], v[56:57], v[152:153]
	s_nop 0
	v_mul_f32_e32 v150, 0xbfb8aa3b, v150
	v_mul_f32_e32 v151, 0xbfb8aa3b, v151
	v_mul_f32_e32 v152, 0xbfb8aa3b, v152
	v_mul_f32_e32 v153, 0xbfb8aa3b, v153
	v_exp_f32_e32 v150, v150
	v_exp_f32_e32 v151, v151
	v_exp_f32_e32 v152, v152
	v_exp_f32_e32 v153, v153
	v_add_f32_e32 v150, 1.0, v150
	v_add_f32_e32 v151, 1.0, v151
	v_add_f32_e32 v152, 1.0, v152
	v_add_f32_e32 v153, 1.0, v153
	v_rcp_f32_e32 v150, v150
	v_rcp_f32_e32 v151, v151
	v_rcp_f32_e32 v152, v152
	v_rcp_f32_e32 v153, v153
	v_pk_mul_f32 v[12:13], v[12:13], v[150:151]
	v_pk_mul_f32 v[14:15], v[14:15], v[152:153]
	s_nop 0
	global_store_dwordx4 v49, v[12:15], s[72:73] offset:0
	s_waitcnt vmcnt(2)
	v_lshlrev_b32_e32 v150, 16, v206
	v_and_b32_e32 v151, 0xffff0000, v206
	v_lshlrev_b32_e32 v152, 16, v207
	v_and_b32_e32 v153, 0xffff0000, v207
	v_pk_add_f32 v[150:151], v[58:59], v[150:151]
	v_pk_add_f32 v[152:153], v[60:61], v[152:153]
	s_nop 0
	v_mul_f32_e32 v150, 0xbfb8aa3b, v150
	v_mul_f32_e32 v151, 0xbfb8aa3b, v151
	v_mul_f32_e32 v152, 0xbfb8aa3b, v152
	v_mul_f32_e32 v153, 0xbfb8aa3b, v153
	v_exp_f32_e32 v150, v150
	v_exp_f32_e32 v151, v151
	v_exp_f32_e32 v152, v152
	v_exp_f32_e32 v153, v153
	v_add_f32_e32 v150, 1.0, v150
	v_add_f32_e32 v151, 1.0, v151
	v_add_f32_e32 v152, 1.0, v152
	v_add_f32_e32 v153, 1.0, v153
	v_rcp_f32_e32 v150, v150
	v_rcp_f32_e32 v151, v151
	v_rcp_f32_e32 v152, v152
	v_rcp_f32_e32 v153, v153
	v_pk_mul_f32 v[8:9], v[8:9], v[150:151]
	v_pk_mul_f32 v[10:11], v[10:11], v[152:153]
	s_nop 0
	global_store_dwordx4 v49, v[8:11], s[72:73] offset:64
	s_waitcnt vmcnt(1)
	v_lshlrev_b32_e32 v150, 16, v208
	v_and_b32_e32 v151, 0xffff0000, v208
	v_lshlrev_b32_e32 v152, 16, v209
	v_and_b32_e32 v153, 0xffff0000, v209
	v_pk_add_f32 v[150:151], v[62:63], v[150:151]
	v_pk_add_f32 v[152:153], v[64:65], v[152:153]
	s_nop 0
	v_mul_f32_e32 v150, 0xbfb8aa3b, v150
	v_mul_f32_e32 v151, 0xbfb8aa3b, v151
	v_mul_f32_e32 v152, 0xbfb8aa3b, v152
	v_mul_f32_e32 v153, 0xbfb8aa3b, v153
	v_exp_f32_e32 v150, v150
	v_exp_f32_e32 v151, v151
	v_exp_f32_e32 v152, v152
	v_exp_f32_e32 v153, v153
	v_add_f32_e32 v150, 1.0, v150
	v_add_f32_e32 v151, 1.0, v151
	v_add_f32_e32 v152, 1.0, v152
	v_add_f32_e32 v153, 1.0, v153
	v_rcp_f32_e32 v150, v150
	v_rcp_f32_e32 v151, v151
	v_rcp_f32_e32 v152, v152
	v_rcp_f32_e32 v153, v153
	v_pk_mul_f32 v[4:5], v[4:5], v[150:151]
	v_pk_mul_f32 v[6:7], v[6:7], v[152:153]
	s_nop 0
	global_store_dwordx4 v49, v[4:7], s[72:73] offset:128
	s_waitcnt vmcnt(0)
	v_lshlrev_b32_e32 v150, 16, v210
	v_and_b32_e32 v151, 0xffff0000, v210
	v_lshlrev_b32_e32 v152, 16, v211
	v_and_b32_e32 v153, 0xffff0000, v211
	v_pk_add_f32 v[150:151], v[66:67], v[150:151]
	v_pk_add_f32 v[152:153], v[68:69], v[152:153]
	s_nop 0
	v_mul_f32_e32 v150, 0xbfb8aa3b, v150
	v_mul_f32_e32 v151, 0xbfb8aa3b, v151
	v_mul_f32_e32 v152, 0xbfb8aa3b, v152
	v_mul_f32_e32 v153, 0xbfb8aa3b, v153
	v_exp_f32_e32 v150, v150
	v_exp_f32_e32 v151, v151
	v_exp_f32_e32 v152, v152
	v_exp_f32_e32 v153, v153
	v_add_f32_e32 v150, 1.0, v150
	v_add_f32_e32 v151, 1.0, v151
	v_add_f32_e32 v152, 1.0, v152
	v_add_f32_e32 v153, 1.0, v153
	v_rcp_f32_e32 v150, v150
	v_rcp_f32_e32 v151, v151
	v_rcp_f32_e32 v152, v152
	v_rcp_f32_e32 v153, v153
	v_pk_mul_f32 v[0:1], v[0:1], v[150:151]
	v_pk_mul_f32 v[2:3], v[2:3], v[152:153]
	s_nop 0
	global_store_dwordx4 v49, v[0:3], s[72:73] offset:192
	v_readlane_b32 s4, v242, 63
	s_nop 3
	s_add_i32 s2, s2, s4
	s_cmpk_gt_i32 s2, 0x57f
	s_cbranch_scc0 .LBB1_807
